# v44 plus the P1 top-of-tile prefetch of ssq rows and gate bias (epilogue issues no global loads)
# speedup vs baseline: 1.0046x; 1.0046x over previous
; __device__ __forceinline__ u32x4 pack8(const float* f) { u32x4 w; w.x = cvt_pk_bf16(f[0], f[1]); w.y = cvt_pk_bf16(f[2], f[3]); w.z = cvt_pk_bf16(f[4], f[5]); w.w = cvt_pk_bf16(f[6], f[7]); return w; }
;     __device__ __forceinline__ void operator()(AccT& acc, const Unit& u, int wr, int wc, int fr, int fq) const {
;     ...
;         float rsv[2][4];
; #pragma unroll
;         for (int ai = 0; ai < 2; ++ai)
; #pragma unroll
;             for (int m = 0; m < 4; ++m) rsv[ai][m] = ssq[u.pm * 256 + ai * 128 + wr * 64 + m * 16 + fr];
; #pragma unroll
;         for (int ai = 0; ai < 2; ++ai)
; #pragma unroll
;             for (int m = 0; m < 4; ++m) {
;                 const int row = u.pm * 256 + ai * 128 + wr * 64 + m * 16 + fr;
;                 const float rs = __builtin_amdgcn_rsqf(rsv[ai][m] * (1.0f / 1024.0f) + EPS);
;                 bf16_t* rowp = P + (size_t)row * INW + col0;
; #pragma unroll
;                 for (int bj = 0; bj < 2; ++bj) {
;                     float v[8];
; #pragma unroll
;                     for (int n = 0; n < 2; ++n)
; #pragma unroll
;                         for (int j = 0; j < 4; ++j) {
;                             float x = acc[ai][bj][m][n][j] * rs;
;                             if (gate) { x += gb[bj][n][j]; x = __builtin_amdgcn_rcpf(1.0f + __builtin_amdgcn_exp2f(-LOG2E * x)); }
;                             v[n * 4 + j] = x;
;                         }
;                     *(u32x4*)(rowp + bj * 128) = pack8(v);
;                 }
.Lmy_p1_nobias:
	s_lshl_b32 s0, s49, 8
	s_add_i32 s0, s0, s33
	v_add_u32_e32 v160, s0, v160
	v_mov_b32_e32 v161, v238
	v_mov_b32_e32 v179, v239
	v_mov_b32_e32 v177, v240
	v_mov_b32_e32 v175, v241
	v_mov_b32_e32 v173, v242
	v_mov_b32_e32 v171, v243
	v_mov_b32_e32 v169, v244
	v_mov_b32_e32 v167, v245
	v_add_u32_e32 v178, 16, v160
	v_add_u32_e32 v176, 32, v160
	v_add_u32_e32 v174, 48, v160
	v_add_u32_e32 v172, 0x80, v160
	v_add_u32_e32 v170, 0x90, v160
	v_add_u32_e32 v168, 0xa0, v160
	v_add_u32_e32 v166, 0xb0, v160
	v_lshlrev_b64 v[158:159], 1, v[158:159]
	s_andn2_b64 vcc, exec, s[40:41]
	s_waitcnt lgkmcnt(0)
	s_cmp_eq_u64 s[42:43], 0
	s_cbranch_scc1 .Lmy_p1_nongate
	v_mul_f32_e32 v214, 0xbfb8aa3b, v52
	v_mul_f32_e32 v215, 0xbfb8aa3b, v53
	v_mul_f32_e32 v216, 0xbfb8aa3b, v54
	v_mul_f32_e32 v217, 0xbfb8aa3b, v55
	v_mul_f32_e32 v218, 0xbfb8aa3b, v44
	v_mul_f32_e32 v219, 0xbfb8aa3b, v45
	v_mul_f32_e32 v220, 0xbfb8aa3b, v46
	v_mul_f32_e32 v221, 0xbfb8aa3b, v47
	v_mul_f32_e32 v234, 0xbfb8aa3b, v40
	v_mul_f32_e32 v235, 0xbfb8aa3b, v41
	v_mul_f32_e32 v236, 0xbfb8aa3b, v42
	v_mul_f32_e32 v237, 0xbfb8aa3b, v43
	v_mul_f32_e32 v250, 0xbfb8aa3b, v32
	v_mul_f32_e32 v251, 0xbfb8aa3b, v33
	v_mul_f32_e32 v252, 0xbfb8aa3b, v34
	v_mul_f32_e32 v253, 0xbfb8aa3b, v35
	v_fmamk_f32 v156, v161, 0x3a800000, v223
	v_rsq_f32_e32 v180, v156
	s_nop 0
	v_mul_f32_e32 v180, 0xbfb8aa3b, v180
	v_mov_b64_e32 v[156:157], s[84:85]
	v_mad_i64_i32 v[160:161], s[0:1], v160, s89, v[156:157]
	v_lshl_add_u64 v[160:161], v[160:161], 0, v[158:159]
	v_fma_f32 v206, v142, v180, v214
	v_fma_f32 v207, v143, v180, v215
	v_fma_f32 v208, v144, v180, v216
	v_fma_f32 v209, v145, v180, v217
	v_fma_f32 v210, v138, v180, v218
	v_fma_f32 v211, v139, v180, v219
	v_fma_f32 v212, v140, v180, v220
	v_fma_f32 v213, v141, v180, v221
	v_exp_f32_e32 v206, v206
	v_exp_f32_e32 v207, v207
	v_exp_f32_e32 v208, v208
	v_exp_f32_e32 v209, v209
	v_exp_f32_e32 v210, v210
	v_exp_f32_e32 v211, v211
	v_exp_f32_e32 v212, v212
	v_exp_f32_e32 v213, v213
	v_add_f32_e32 v206, 1.0, v206
	v_add_f32_e32 v207, 1.0, v207
	v_add_f32_e32 v208, 1.0, v208
	v_add_f32_e32 v209, 1.0, v209
	v_add_f32_e32 v210, 1.0, v210
	v_add_f32_e32 v211, 1.0, v211
	v_add_f32_e32 v212, 1.0, v212
	v_add_f32_e32 v213, 1.0, v213
	v_rcp_f32_e32 v142, v206
	v_rcp_f32_e32 v143, v207
	v_rcp_f32_e32 v144, v208
	v_rcp_f32_e32 v145, v209
	v_rcp_f32_e32 v181, v210
	v_rcp_f32_e32 v182, v211
	v_rcp_f32_e32 v183, v212
	v_rcp_f32_e32 v141, v213
	v_cvt_pk_bf16_f32 v138, v142, v143
	v_cvt_pk_bf16_f32 v139, v144, v145
	v_cvt_pk_bf16_f32 v140, v181, v182
	v_cvt_pk_bf16_f32 v141, v183, v141
	global_store_dwordx4 v[160:161], v[138:141], off nt
	s_nop 1
	v_fma_f32 v206, v134, v180, v234
	v_fma_f32 v207, v135, v180, v235
	v_fma_f32 v208, v136, v180, v236
	v_fma_f32 v209, v137, v180, v237
	v_fma_f32 v210, v130, v180, v250
	v_fma_f32 v211, v131, v180, v251
	v_fma_f32 v212, v132, v180, v252
	v_fma_f32 v213, v133, v180, v253
	v_exp_f32_e32 v206, v206
	v_exp_f32_e32 v207, v207
	v_exp_f32_e32 v208, v208
	v_exp_f32_e32 v209, v209
	v_exp_f32_e32 v210, v210
	v_exp_f32_e32 v211, v211
	v_exp_f32_e32 v212, v212
	v_exp_f32_e32 v213, v213
	v_add_f32_e32 v206, 1.0, v206
	v_add_f32_e32 v207, 1.0, v207
	v_add_f32_e32 v208, 1.0, v208
	v_add_f32_e32 v209, 1.0, v209
	v_add_f32_e32 v210, 1.0, v210
	v_add_f32_e32 v211, 1.0, v211
	v_add_f32_e32 v212, 1.0, v212
	v_add_f32_e32 v213, 1.0, v213
	v_rcp_f32_e32 v134, v206
	v_rcp_f32_e32 v135, v207
	v_rcp_f32_e32 v136, v208
	v_rcp_f32_e32 v137, v209
	v_rcp_f32_e32 v138, v210
	v_rcp_f32_e32 v139, v211
	v_rcp_f32_e32 v140, v212
	v_rcp_f32_e32 v133, v213
	v_cvt_pk_bf16_f32 v130, v134, v135
	v_cvt_pk_bf16_f32 v131, v136, v137
	v_cvt_pk_bf16_f32 v132, v138, v139
	v_cvt_pk_bf16_f32 v133, v140, v133
	global_store_dwordx4 v[160:161], v[130:133], off offset:256 nt
	s_nop 1
	v_fmamk_f32 v130, v179, 0x3a800000, v223
	v_rsq_f32_e32 v132, v130
	s_nop 0
	v_mul_f32_e32 v132, 0xbfb8aa3b, v132
	v_mad_i64_i32 v[130:131], s[0:1], v178, s89, v[156:157]
	v_lshl_add_u64 v[130:131], v[130:131], 0, v[158:159]
	v_fma_f32 v206, v126, v132, v214
	v_fma_f32 v207, v127, v132, v215
	v_fma_f32 v208, v128, v132, v216
	v_fma_f32 v209, v129, v132, v217
	v_fma_f32 v210, v122, v132, v218
	v_fma_f32 v211, v123, v132, v219
	v_fma_f32 v212, v124, v132, v220
	v_fma_f32 v213, v125, v132, v221
	v_exp_f32_e32 v206, v206
	v_exp_f32_e32 v207, v207
	v_exp_f32_e32 v208, v208
	v_exp_f32_e32 v209, v209
	v_exp_f32_e32 v210, v210
	v_exp_f32_e32 v211, v211
	v_exp_f32_e32 v212, v212
	v_exp_f32_e32 v213, v213
	v_add_f32_e32 v206, 1.0, v206
	v_add_f32_e32 v207, 1.0, v207
	v_add_f32_e32 v208, 1.0, v208
	v_add_f32_e32 v209, 1.0, v209
	v_add_f32_e32 v210, 1.0, v210
	v_add_f32_e32 v211, 1.0, v211
	v_add_f32_e32 v212, 1.0, v212
	v_add_f32_e32 v213, 1.0, v213
	v_rcp_f32_e32 v126, v206
	v_rcp_f32_e32 v127, v207
	v_rcp_f32_e32 v128, v208
	v_rcp_f32_e32 v129, v209
	v_rcp_f32_e32 v133, v210
	v_rcp_f32_e32 v134, v211
	v_rcp_f32_e32 v135, v212
	v_rcp_f32_e32 v125, v213
	v_cvt_pk_bf16_f32 v122, v126, v127
	v_cvt_pk_bf16_f32 v123, v128, v129
	v_cvt_pk_bf16_f32 v124, v133, v134
	v_cvt_pk_bf16_f32 v125, v135, v125
	global_store_dwordx4 v[130:131], v[122:125], off nt
	s_nop 1
	v_fma_f32 v206, v118, v132, v234
	v_fma_f32 v207, v119, v132, v235
	v_fma_f32 v208, v120, v132, v236
	v_fma_f32 v209, v121, v132, v237
	v_fma_f32 v210, v114, v132, v250
	v_fma_f32 v211, v115, v132, v251
	v_fma_f32 v212, v116, v132, v252
	v_fma_f32 v213, v117, v132, v253
	v_exp_f32_e32 v206, v206
	v_exp_f32_e32 v207, v207
	v_exp_f32_e32 v208, v208
	v_exp_f32_e32 v209, v209
	v_exp_f32_e32 v210, v210
	v_exp_f32_e32 v211, v211
	v_exp_f32_e32 v212, v212
; __device__ __forceinline__ u32x4 pack8(const float* f) { u32x4 w; w.x = cvt_pk_bf16(f[0], f[1]); w.y = cvt_pk_bf16(f[2], f[3]); w.z = cvt_pk_bf16(f[4], f[5]); w.w = cvt_pk_bf16(f[6], f[7]); return w; }
;     __device__ __forceinline__ void operator()(AccT& acc, const Unit& u, int wr, int wc, int fr, int fq) const {
;     ...
;         for (int ai = 0; ai < 2; ++ai)
; #pragma unroll
;             for (int m = 0; m < 4; ++m) {
;                 const int row = u.pm * 256 + ai * 128 + wr * 64 + m * 16 + fr;
;                 const float rs = __builtin_amdgcn_rsqf(rsv[ai][m] * (1.0f / 1024.0f) + EPS);
;                 bf16_t* rowp = P + (size_t)row * INW + col0;
; #pragma unroll
;                 for (int bj = 0; bj < 2; ++bj) {
;                     float v[8];
; #pragma unroll
;                     for (int n = 0; n < 2; ++n)
; #pragma unroll
;                         for (int j = 0; j < 4; ++j) {
;                             float x = acc[ai][bj][m][n][j] * rs;
;                             if (gate) { x += gb[bj][n][j]; x = __builtin_amdgcn_rcpf(1.0f + __builtin_amdgcn_exp2f(-LOG2E * x)); }
;                             v[n * 4 + j] = x;
;                         }
;                     *(u32x4*)(rowp + bj * 128) = pack8(v);
;                 }
	v_exp_f32_e32 v213, v213
	v_add_f32_e32 v206, 1.0, v206
	v_add_f32_e32 v207, 1.0, v207
	v_add_f32_e32 v208, 1.0, v208
	v_add_f32_e32 v209, 1.0, v209
	v_add_f32_e32 v210, 1.0, v210
	v_add_f32_e32 v211, 1.0, v211
	v_add_f32_e32 v212, 1.0, v212
	v_add_f32_e32 v213, 1.0, v213
	v_rcp_f32_e32 v118, v206
	v_rcp_f32_e32 v119, v207
	v_rcp_f32_e32 v120, v208
	v_rcp_f32_e32 v121, v209
	v_rcp_f32_e32 v122, v210
	v_rcp_f32_e32 v123, v211
	v_rcp_f32_e32 v124, v212
	v_rcp_f32_e32 v117, v213
	v_cvt_pk_bf16_f32 v114, v118, v119
	v_cvt_pk_bf16_f32 v115, v120, v121
	v_cvt_pk_bf16_f32 v116, v122, v123
	v_cvt_pk_bf16_f32 v117, v124, v117
	global_store_dwordx4 v[130:131], v[114:117], off offset:256 nt
	s_nop 1
	v_fmamk_f32 v114, v177, 0x3a800000, v223
	v_rsq_f32_e32 v116, v114
	s_nop 0
	v_mul_f32_e32 v116, 0xbfb8aa3b, v116
	v_mad_i64_i32 v[114:115], s[0:1], v176, s89, v[156:157]
	v_lshl_add_u64 v[114:115], v[114:115], 0, v[158:159]
	v_fma_f32 v206, v110, v116, v214
	v_fma_f32 v207, v111, v116, v215
	v_fma_f32 v208, v112, v116, v216
	v_fma_f32 v209, v113, v116, v217
	v_fma_f32 v210, v106, v116, v218
	v_fma_f32 v211, v107, v116, v219
	v_fma_f32 v212, v108, v116, v220
	v_fma_f32 v213, v109, v116, v221
	v_exp_f32_e32 v206, v206
	v_exp_f32_e32 v207, v207
	v_exp_f32_e32 v208, v208
	v_exp_f32_e32 v209, v209
	v_exp_f32_e32 v210, v210
	v_exp_f32_e32 v211, v211
	v_exp_f32_e32 v212, v212
	v_exp_f32_e32 v213, v213
	v_add_f32_e32 v206, 1.0, v206
	v_add_f32_e32 v207, 1.0, v207
	v_add_f32_e32 v208, 1.0, v208
	v_add_f32_e32 v209, 1.0, v209
	v_add_f32_e32 v210, 1.0, v210
	v_add_f32_e32 v211, 1.0, v211
	v_add_f32_e32 v212, 1.0, v212
	v_add_f32_e32 v213, 1.0, v213
	v_rcp_f32_e32 v110, v206
	v_rcp_f32_e32 v111, v207
	v_rcp_f32_e32 v112, v208
	v_rcp_f32_e32 v113, v209
	v_rcp_f32_e32 v117, v210
	v_rcp_f32_e32 v118, v211
	v_rcp_f32_e32 v119, v212
	v_rcp_f32_e32 v109, v213
	v_cvt_pk_bf16_f32 v106, v110, v111
	v_cvt_pk_bf16_f32 v107, v112, v113
	v_cvt_pk_bf16_f32 v108, v117, v118
	v_cvt_pk_bf16_f32 v109, v119, v109
	global_store_dwordx4 v[114:115], v[106:109], off nt
	s_nop 1
	v_fma_f32 v206, v102, v116, v234
	v_fma_f32 v207, v103, v116, v235
	v_fma_f32 v208, v104, v116, v236
	v_fma_f32 v209, v105, v116, v237
	v_fma_f32 v210, v98, v116, v250
	v_fma_f32 v211, v99, v116, v251
	v_fma_f32 v212, v100, v116, v252
	v_fma_f32 v213, v101, v116, v253
	v_exp_f32_e32 v206, v206
	v_exp_f32_e32 v207, v207
	v_exp_f32_e32 v208, v208
	v_exp_f32_e32 v209, v209
	v_exp_f32_e32 v210, v210
	v_exp_f32_e32 v211, v211
	v_exp_f32_e32 v212, v212
	v_exp_f32_e32 v213, v213
	v_add_f32_e32 v206, 1.0, v206
	v_add_f32_e32 v207, 1.0, v207
	v_add_f32_e32 v208, 1.0, v208
	v_add_f32_e32 v209, 1.0, v209
	v_add_f32_e32 v210, 1.0, v210
	v_add_f32_e32 v211, 1.0, v211
	v_add_f32_e32 v212, 1.0, v212
	v_add_f32_e32 v213, 1.0, v213
	v_rcp_f32_e32 v102, v206
	v_rcp_f32_e32 v103, v207
	v_rcp_f32_e32 v104, v208
	v_rcp_f32_e32 v105, v209
	v_rcp_f32_e32 v106, v210
	v_rcp_f32_e32 v107, v211
	v_rcp_f32_e32 v108, v212
	v_rcp_f32_e32 v101, v213
	v_cvt_pk_bf16_f32 v98, v102, v103
	v_cvt_pk_bf16_f32 v99, v104, v105
	v_cvt_pk_bf16_f32 v100, v106, v107
	v_cvt_pk_bf16_f32 v101, v108, v101
	global_store_dwordx4 v[114:115], v[98:101], off offset:256 nt
	s_nop 1
	v_fmamk_f32 v98, v175, 0x3a800000, v223
	v_rsq_f32_e32 v100, v98
	s_nop 0
	v_mul_f32_e32 v100, 0xbfb8aa3b, v100
	v_mad_i64_i32 v[98:99], s[0:1], v174, s89, v[156:157]
	v_lshl_add_u64 v[98:99], v[98:99], 0, v[158:159]
	v_fma_f32 v206, v92, v100, v214
	v_fma_f32 v207, v93, v100, v215
	v_fma_f32 v208, v94, v100, v216
	v_fma_f32 v209, v95, v100, v217
	v_fma_f32 v210, v88, v100, v218
	v_fma_f32 v211, v89, v100, v219
	v_fma_f32 v212, v90, v100, v220
	v_fma_f32 v213, v91, v100, v221
	v_exp_f32_e32 v206, v206
	v_exp_f32_e32 v207, v207
	v_exp_f32_e32 v208, v208
	v_exp_f32_e32 v209, v209
	v_exp_f32_e32 v210, v210
	v_exp_f32_e32 v211, v211
	v_exp_f32_e32 v212, v212
	v_exp_f32_e32 v213, v213
	v_add_f32_e32 v206, 1.0, v206
	v_add_f32_e32 v207, 1.0, v207
	v_add_f32_e32 v208, 1.0, v208
	v_add_f32_e32 v209, 1.0, v209
	v_add_f32_e32 v210, 1.0, v210
	v_add_f32_e32 v211, 1.0, v211
	v_add_f32_e32 v212, 1.0, v212
	v_add_f32_e32 v213, 1.0, v213
	v_rcp_f32_e32 v92, v206
	v_rcp_f32_e32 v93, v207
	v_rcp_f32_e32 v94, v208
	v_rcp_f32_e32 v95, v209
	v_rcp_f32_e32 v101, v210
	v_rcp_f32_e32 v102, v211
	v_rcp_f32_e32 v103, v212
	v_rcp_f32_e32 v91, v213
	v_cvt_pk_bf16_f32 v88, v92, v93
	v_cvt_pk_bf16_f32 v89, v94, v95
	v_cvt_pk_bf16_f32 v90, v101, v102
	v_cvt_pk_bf16_f32 v91, v103, v91
	global_store_dwordx4 v[98:99], v[88:91], off nt
	s_nop 1
	v_fma_f32 v206, v84, v100, v234
	v_fma_f32 v207, v85, v100, v235
	v_fma_f32 v208, v86, v100, v236
	v_fma_f32 v209, v87, v100, v237
	v_fma_f32 v210, v80, v100, v250
	v_fma_f32 v211, v81, v100, v251
	v_fma_f32 v212, v82, v100, v252
	v_fma_f32 v213, v83, v100, v253
	v_exp_f32_e32 v206, v206
	v_exp_f32_e32 v207, v207
	v_exp_f32_e32 v208, v208
	v_exp_f32_e32 v209, v209
	v_exp_f32_e32 v210, v210
	v_exp_f32_e32 v211, v211
	v_exp_f32_e32 v212, v212
	v_exp_f32_e32 v213, v213
	v_add_f32_e32 v206, 1.0, v206
	v_add_f32_e32 v207, 1.0, v207
	v_add_f32_e32 v208, 1.0, v208
	v_add_f32_e32 v209, 1.0, v209
	v_add_f32_e32 v210, 1.0, v210
	v_add_f32_e32 v211, 1.0, v211
	v_add_f32_e32 v212, 1.0, v212
	v_add_f32_e32 v213, 1.0, v213
	v_rcp_f32_e32 v84, v206
	v_rcp_f32_e32 v85, v207
	v_rcp_f32_e32 v86, v208
	v_rcp_f32_e32 v87, v209
	v_rcp_f32_e32 v88, v210
	v_rcp_f32_e32 v89, v211
	v_rcp_f32_e32 v90, v212
	v_rcp_f32_e32 v83, v213
	v_cvt_pk_bf16_f32 v80, v84, v85
	v_cvt_pk_bf16_f32 v81, v86, v87
	v_cvt_pk_bf16_f32 v82, v88, v89
	v_cvt_pk_bf16_f32 v83, v90, v83
	global_store_dwordx4 v[98:99], v[80:83], off offset:256 nt
; __device__ __forceinline__ u32x4 pack8(const float* f) { u32x4 w; w.x = cvt_pk_bf16(f[0], f[1]); w.y = cvt_pk_bf16(f[2], f[3]); w.z = cvt_pk_bf16(f[4], f[5]); w.w = cvt_pk_bf16(f[6], f[7]); return w; }
;     __device__ __forceinline__ void operator()(AccT& acc, const Unit& u, int wr, int wc, int fr, int fq) const {
;     ...
;         for (int ai = 0; ai < 2; ++ai)
; #pragma unroll
;             for (int m = 0; m < 4; ++m) {
;                 const int row = u.pm * 256 + ai * 128 + wr * 64 + m * 16 + fr;
;                 const float rs = __builtin_amdgcn_rsqf(rsv[ai][m] * (1.0f / 1024.0f) + EPS);
;                 bf16_t* rowp = P + (size_t)row * INW + col0;
; #pragma unroll
;                 for (int bj = 0; bj < 2; ++bj) {
;                     float v[8];
; #pragma unroll
;                     for (int n = 0; n < 2; ++n)
; #pragma unroll
;                         for (int j = 0; j < 4; ++j) {
;                             float x = acc[ai][bj][m][n][j] * rs;
;                             if (gate) { x += gb[bj][n][j]; x = __builtin_amdgcn_rcpf(1.0f + __builtin_amdgcn_exp2f(-LOG2E * x)); }
;                             v[n * 4 + j] = x;
;                         }
;                     *(u32x4*)(rowp + bj * 128) = pack8(v);
;                 }
	s_nop 1
	v_fmamk_f32 v80, v173, 0x3a800000, v223
	v_rsq_f32_e32 v82, v80
	s_nop 0
	v_mul_f32_e32 v82, 0xbfb8aa3b, v82
	v_mad_i64_i32 v[80:81], s[0:1], v172, s89, v[156:157]
	v_lshl_add_u64 v[80:81], v[80:81], 0, v[158:159]
	v_fma_f32 v206, v76, v82, v214
	v_fma_f32 v207, v77, v82, v215
	v_fma_f32 v208, v78, v82, v216
	v_fma_f32 v209, v79, v82, v217
	v_fma_f32 v210, v72, v82, v218
	v_fma_f32 v211, v73, v82, v219
	v_fma_f32 v212, v74, v82, v220
	v_fma_f32 v213, v75, v82, v221
	v_exp_f32_e32 v206, v206
	v_exp_f32_e32 v207, v207
	v_exp_f32_e32 v208, v208
	v_exp_f32_e32 v209, v209
	v_exp_f32_e32 v210, v210
	v_exp_f32_e32 v211, v211
	v_exp_f32_e32 v212, v212
	v_exp_f32_e32 v213, v213
	v_add_f32_e32 v206, 1.0, v206
	v_add_f32_e32 v207, 1.0, v207
	v_add_f32_e32 v208, 1.0, v208
	v_add_f32_e32 v209, 1.0, v209
	v_add_f32_e32 v210, 1.0, v210
	v_add_f32_e32 v211, 1.0, v211
	v_add_f32_e32 v212, 1.0, v212
	v_add_f32_e32 v213, 1.0, v213
	v_rcp_f32_e32 v76, v206
	v_rcp_f32_e32 v77, v207
	v_rcp_f32_e32 v78, v208
	v_rcp_f32_e32 v79, v209
	v_rcp_f32_e32 v83, v210
	v_rcp_f32_e32 v84, v211
	v_rcp_f32_e32 v85, v212
	v_rcp_f32_e32 v75, v213
	v_cvt_pk_bf16_f32 v72, v76, v77
	v_cvt_pk_bf16_f32 v73, v78, v79
	v_cvt_pk_bf16_f32 v74, v83, v84
	v_cvt_pk_bf16_f32 v75, v85, v75
	global_store_dwordx4 v[80:81], v[72:75], off nt
	s_nop 1
	v_fma_f32 v206, v68, v82, v234
	v_fma_f32 v207, v69, v82, v235
	v_fma_f32 v208, v70, v82, v236
	v_fma_f32 v209, v71, v82, v237
	v_fma_f32 v210, v64, v82, v250
	v_fma_f32 v211, v65, v82, v251
	v_fma_f32 v212, v66, v82, v252
	v_fma_f32 v213, v67, v82, v253
	v_exp_f32_e32 v206, v206
	v_exp_f32_e32 v207, v207
	v_exp_f32_e32 v208, v208
	v_exp_f32_e32 v209, v209
	v_exp_f32_e32 v210, v210
	v_exp_f32_e32 v211, v211
	v_exp_f32_e32 v212, v212
	v_exp_f32_e32 v213, v213
	v_add_f32_e32 v206, 1.0, v206
	v_add_f32_e32 v207, 1.0, v207
	v_add_f32_e32 v208, 1.0, v208
	v_add_f32_e32 v209, 1.0, v209
	v_add_f32_e32 v210, 1.0, v210
	v_add_f32_e32 v211, 1.0, v211
	v_add_f32_e32 v212, 1.0, v212
	v_add_f32_e32 v213, 1.0, v213
	v_rcp_f32_e32 v68, v206
	v_rcp_f32_e32 v69, v207
	v_rcp_f32_e32 v70, v208
	v_rcp_f32_e32 v71, v209
	v_rcp_f32_e32 v72, v210
	v_rcp_f32_e32 v73, v211
	v_rcp_f32_e32 v74, v212
	v_rcp_f32_e32 v67, v213
	v_cvt_pk_bf16_f32 v64, v68, v69
	v_cvt_pk_bf16_f32 v65, v70, v71
	v_cvt_pk_bf16_f32 v66, v72, v73
	v_cvt_pk_bf16_f32 v67, v74, v67
	global_store_dwordx4 v[80:81], v[64:67], off offset:256 nt
	s_nop 1
	v_fmamk_f32 v64, v171, 0x3a800000, v223
	v_rsq_f32_e32 v66, v64
	s_nop 0
	v_mul_f32_e32 v66, 0xbfb8aa3b, v66
	v_mad_i64_i32 v[64:65], s[0:1], v170, s89, v[156:157]
	v_lshl_add_u64 v[64:65], v[64:65], 0, v[158:159]
	v_fma_f32 v206, v60, v66, v214
	v_fma_f32 v207, v61, v66, v215
	v_fma_f32 v208, v62, v66, v216
	v_fma_f32 v209, v63, v66, v217
	v_fma_f32 v210, v56, v66, v218
	v_fma_f32 v211, v57, v66, v219
	v_fma_f32 v212, v58, v66, v220
	v_fma_f32 v213, v59, v66, v221
	v_exp_f32_e32 v206, v206
	v_exp_f32_e32 v207, v207
	v_exp_f32_e32 v208, v208
	v_exp_f32_e32 v209, v209
	v_exp_f32_e32 v210, v210
	v_exp_f32_e32 v211, v211
	v_exp_f32_e32 v212, v212
	v_exp_f32_e32 v213, v213
	v_add_f32_e32 v206, 1.0, v206
	v_add_f32_e32 v207, 1.0, v207
	v_add_f32_e32 v208, 1.0, v208
	v_add_f32_e32 v209, 1.0, v209
	v_add_f32_e32 v210, 1.0, v210
	v_add_f32_e32 v211, 1.0, v211
	v_add_f32_e32 v212, 1.0, v212
	v_add_f32_e32 v213, 1.0, v213
	v_rcp_f32_e32 v60, v206
	v_rcp_f32_e32 v61, v207
	v_rcp_f32_e32 v62, v208
	v_rcp_f32_e32 v63, v209
	v_rcp_f32_e32 v67, v210
	v_rcp_f32_e32 v68, v211
	v_rcp_f32_e32 v69, v212
	v_rcp_f32_e32 v59, v213
	v_cvt_pk_bf16_f32 v56, v60, v61
	v_cvt_pk_bf16_f32 v57, v62, v63
	v_cvt_pk_bf16_f32 v58, v67, v68
	v_cvt_pk_bf16_f32 v59, v69, v59
	global_store_dwordx4 v[64:65], v[56:59], off nt
	s_nop 1
	v_fma_f32 v206, v48, v66, v234
	v_fma_f32 v207, v49, v66, v235
	v_fma_f32 v208, v50, v66, v236
	v_fma_f32 v209, v51, v66, v237
	v_fma_f32 v210, v36, v66, v250
	v_fma_f32 v211, v37, v66, v251
	v_fma_f32 v212, v38, v66, v252
	v_fma_f32 v213, v39, v66, v253
	v_exp_f32_e32 v206, v206
	v_exp_f32_e32 v207, v207
	v_exp_f32_e32 v208, v208
	v_exp_f32_e32 v209, v209
	v_exp_f32_e32 v210, v210
	v_exp_f32_e32 v211, v211
	v_exp_f32_e32 v212, v212
	v_exp_f32_e32 v213, v213
	v_add_f32_e32 v206, 1.0, v206
	v_add_f32_e32 v207, 1.0, v207
	v_add_f32_e32 v208, 1.0, v208
	v_add_f32_e32 v209, 1.0, v209
	v_add_f32_e32 v210, 1.0, v210
	v_add_f32_e32 v211, 1.0, v211
	v_add_f32_e32 v212, 1.0, v212
	v_add_f32_e32 v213, 1.0, v213
	v_rcp_f32_e32 v48, v206
	v_rcp_f32_e32 v49, v207
	v_rcp_f32_e32 v50, v208
	v_rcp_f32_e32 v51, v209
	v_rcp_f32_e32 v56, v210
	v_rcp_f32_e32 v57, v211
	v_rcp_f32_e32 v58, v212
	v_rcp_f32_e32 v39, v213
	v_cvt_pk_bf16_f32 v36, v48, v49
	v_cvt_pk_bf16_f32 v37, v50, v51
	v_cvt_pk_bf16_f32 v38, v56, v57
	v_cvt_pk_bf16_f32 v39, v58, v39
	global_store_dwordx4 v[64:65], v[36:39], off offset:256 nt
	s_nop 1
	v_fmamk_f32 v36, v169, 0x3a800000, v223
	v_rsq_f32_e32 v38, v36
	s_nop 0
	v_mul_f32_e32 v38, 0xbfb8aa3b, v38
	v_mad_i64_i32 v[36:37], s[0:1], v168, s89, v[156:157]
	v_lshl_add_u64 v[36:37], v[36:37], 0, v[158:159]
	v_fma_f32 v206, v28, v38, v214
	v_fma_f32 v207, v29, v38, v215
	v_fma_f32 v208, v30, v38, v216
	v_fma_f32 v209, v31, v38, v217
	v_fma_f32 v210, v24, v38, v218
	v_fma_f32 v211, v25, v38, v219
	v_fma_f32 v212, v26, v38, v220
	v_fma_f32 v213, v27, v38, v221
	v_exp_f32_e32 v206, v206
	v_exp_f32_e32 v207, v207
	v_exp_f32_e32 v208, v208
	v_exp_f32_e32 v209, v209
	v_exp_f32_e32 v210, v210
	v_exp_f32_e32 v211, v211
	v_exp_f32_e32 v212, v212
	v_exp_f32_e32 v213, v213
	v_add_f32_e32 v206, 1.0, v206
	v_add_f32_e32 v207, 1.0, v207
	v_add_f32_e32 v208, 1.0, v208
; __device__ __forceinline__ u32x4 pack8(const float* f) { u32x4 w; w.x = cvt_pk_bf16(f[0], f[1]); w.y = cvt_pk_bf16(f[2], f[3]); w.z = cvt_pk_bf16(f[4], f[5]); w.w = cvt_pk_bf16(f[6], f[7]); return w; }
;     __device__ __forceinline__ void operator()(AccT& acc, const Unit& u, int wr, int wc, int fr, int fq) const {
;     ...
;         for (int ai = 0; ai < 2; ++ai)
; #pragma unroll
;             for (int m = 0; m < 4; ++m) {
;                 const int row = u.pm * 256 + ai * 128 + wr * 64 + m * 16 + fr;
;                 const float rs = __builtin_amdgcn_rsqf(rsv[ai][m] * (1.0f / 1024.0f) + EPS);
;                 bf16_t* rowp = P + (size_t)row * INW + col0;
; #pragma unroll
;                 for (int bj = 0; bj < 2; ++bj) {
;                     float v[8];
; #pragma unroll
;                     for (int n = 0; n < 2; ++n)
; #pragma unroll
;                         for (int j = 0; j < 4; ++j) {
;                             float x = acc[ai][bj][m][n][j] * rs;
;                             if (gate) { x += gb[bj][n][j]; x = __builtin_amdgcn_rcpf(1.0f + __builtin_amdgcn_exp2f(-LOG2E * x)); }
;                             v[n * 4 + j] = x;
;                         }
;                     *(u32x4*)(rowp + bj * 128) = pack8(v);
;                 }
	v_add_f32_e32 v209, 1.0, v209
	v_add_f32_e32 v210, 1.0, v210
	v_add_f32_e32 v211, 1.0, v211
	v_add_f32_e32 v212, 1.0, v212
	v_add_f32_e32 v213, 1.0, v213
	v_rcp_f32_e32 v28, v206
	v_rcp_f32_e32 v29, v207
	v_rcp_f32_e32 v30, v208
	v_rcp_f32_e32 v31, v209
	v_rcp_f32_e32 v39, v210
	v_rcp_f32_e32 v48, v211
	v_rcp_f32_e32 v49, v212
	v_rcp_f32_e32 v27, v213
	v_cvt_pk_bf16_f32 v24, v28, v29
	v_cvt_pk_bf16_f32 v25, v30, v31
	v_cvt_pk_bf16_f32 v26, v39, v48
	v_cvt_pk_bf16_f32 v27, v49, v27
	global_store_dwordx4 v[36:37], v[24:27], off nt
	s_nop 1
	v_fma_f32 v206, v20, v38, v234
	v_fma_f32 v207, v21, v38, v235
	v_fma_f32 v208, v22, v38, v236
	v_fma_f32 v209, v23, v38, v237
	v_fma_f32 v210, v16, v38, v250
	v_fma_f32 v211, v17, v38, v251
	v_fma_f32 v212, v18, v38, v252
	v_fma_f32 v213, v19, v38, v253
	v_exp_f32_e32 v206, v206
	v_exp_f32_e32 v207, v207
	v_exp_f32_e32 v208, v208
	v_exp_f32_e32 v209, v209
	v_exp_f32_e32 v210, v210
	v_exp_f32_e32 v211, v211
	v_exp_f32_e32 v212, v212
	v_exp_f32_e32 v213, v213
	v_add_f32_e32 v206, 1.0, v206
	v_add_f32_e32 v207, 1.0, v207
	v_add_f32_e32 v208, 1.0, v208
	v_add_f32_e32 v209, 1.0, v209
	v_add_f32_e32 v210, 1.0, v210
	v_add_f32_e32 v211, 1.0, v211
	v_add_f32_e32 v212, 1.0, v212
	v_add_f32_e32 v213, 1.0, v213
	v_rcp_f32_e32 v20, v206
	v_rcp_f32_e32 v21, v207
	v_rcp_f32_e32 v22, v208
	v_rcp_f32_e32 v23, v209
	v_rcp_f32_e32 v24, v210
	v_rcp_f32_e32 v25, v211
	v_rcp_f32_e32 v26, v212
	v_rcp_f32_e32 v19, v213
	v_cvt_pk_bf16_f32 v16, v20, v21
	v_cvt_pk_bf16_f32 v17, v22, v23
	v_cvt_pk_bf16_f32 v18, v24, v25
	v_cvt_pk_bf16_f32 v19, v26, v19
	global_store_dwordx4 v[36:37], v[16:19], off offset:256 nt
	s_nop 1
	v_fmamk_f32 v16, v167, 0x3a800000, v223
	v_rsq_f32_e32 v18, v16
	v_mad_i64_i32 v[16:17], s[0:1], v166, s89, v[156:157]
	v_lshl_add_u64 v[16:17], v[16:17], 0, v[158:159]
	v_fmac_f32_e32 v52, v12, v18
	v_mul_f32_e32 v19, v12, v18
	v_mul_f32_e32 v12, 0xbfb8aa3b, v52
	v_exp_f32_e32 v12, v12
	v_fmac_f32_e32 v53, v13, v18
	v_fmac_f32_e32 v54, v14, v18
	v_fmac_f32_e32 v55, v15, v18
	v_add_f32_e32 v12, 1.0, v12
	v_rcp_f32_e32 v12, v12
	v_fmac_f32_e32 v44, v8, v18
	v_fmac_f32_e32 v45, v9, v18
	v_fmac_f32_e32 v46, v10, v18
	v_cndmask_b32_e64 v12, v19, v12, s[42:43]
	v_mul_f32_e32 v19, v13, v18
	v_mul_f32_e32 v13, 0xbfb8aa3b, v53
	v_exp_f32_e32 v13, v13
	v_fmac_f32_e32 v47, v11, v18
	v_fmac_f32_e32 v40, v4, v18
	v_fmac_f32_e32 v41, v5, v18
	v_add_f32_e32 v13, 1.0, v13
	v_rcp_f32_e32 v13, v13
	v_fmac_f32_e32 v42, v6, v18
	v_fmac_f32_e32 v43, v7, v18
	v_fmac_f32_e32 v32, v0, v18
	v_cndmask_b32_e64 v13, v19, v13, s[42:43]
	v_mul_f32_e32 v19, v14, v18
	v_mul_f32_e32 v14, 0xbfb8aa3b, v54
	v_exp_f32_e32 v14, v14
	v_fmac_f32_e32 v33, v1, v18
	v_fmac_f32_e32 v34, v2, v18
	v_fmac_f32_e32 v35, v3, v18
	v_add_f32_e32 v14, 1.0, v14
	v_rcp_f32_e32 v14, v14
	s_mov_b64 s[0:1], -1
	v_cndmask_b32_e64 v14, v19, v14, s[42:43]
	v_mul_f32_e32 v19, v15, v18
	v_mul_f32_e32 v15, 0xbfb8aa3b, v55
	v_exp_f32_e32 v15, v15
	s_nop 0
	v_add_f32_e32 v15, 1.0, v15
	v_rcp_f32_e32 v15, v15
	s_nop 0
	v_cndmask_b32_e64 v15, v19, v15, s[42:43]
	v_mul_f32_e32 v19, v8, v18
	v_mul_f32_e32 v8, 0xbfb8aa3b, v44
	v_exp_f32_e32 v8, v8
	s_nop 0
	v_add_f32_e32 v8, 1.0, v8
	v_rcp_f32_e32 v8, v8
	s_nop 0
	v_cndmask_b32_e64 v19, v19, v8, s[42:43]
	v_mul_f32_e32 v8, v9, v18
	v_mul_f32_e32 v9, 0xbfb8aa3b, v45
	v_exp_f32_e32 v9, v9
	s_nop 0
	v_add_f32_e32 v9, 1.0, v9
	v_rcp_f32_e32 v9, v9
	s_nop 0
	v_cndmask_b32_e64 v20, v8, v9, s[42:43]
	v_mul_f32_e32 v9, 0xbfb8aa3b, v46
	v_exp_f32_e32 v9, v9
	v_mul_f32_e32 v8, v10, v18
	v_add_f32_e32 v9, 1.0, v9
	v_rcp_f32_e32 v9, v9
	s_nop 0
	v_cndmask_b32_e64 v21, v8, v9, s[42:43]
	v_mul_f32_e32 v9, 0xbfb8aa3b, v47
	v_exp_f32_e32 v9, v9
	v_mul_f32_e32 v8, v11, v18
	v_add_f32_e32 v9, 1.0, v9
	v_rcp_f32_e32 v9, v9
	s_nop 0
	v_cndmask_b32_e64 v11, v8, v9, s[42:43]
	v_cvt_pk_bf16_f32 v8, v12, v13
	v_cvt_pk_bf16_f32 v9, v14, v15
	v_cvt_pk_bf16_f32 v10, v19, v20
	v_cvt_pk_bf16_f32 v11, v21, v11
	global_store_dwordx4 v[16:17], v[8:11], off nt
	s_nop 1
	v_mul_f32_e32 v8, v4, v18
	v_mul_f32_e32 v4, 0xbfb8aa3b, v40
	v_exp_f32_e32 v4, v4
	s_nop 0
	v_add_f32_e32 v4, 1.0, v4
	v_rcp_f32_e32 v4, v4
	s_nop 0
	v_cndmask_b32_e64 v4, v8, v4, s[42:43]
	v_mul_f32_e32 v8, v5, v18
	v_mul_f32_e32 v5, 0xbfb8aa3b, v41
	v_exp_f32_e32 v5, v5
	s_nop 0
	v_add_f32_e32 v5, 1.0, v5
	v_rcp_f32_e32 v5, v5
	s_nop 0
	v_cndmask_b32_e64 v5, v8, v5, s[42:43]
	v_mul_f32_e32 v8, v6, v18
	v_mul_f32_e32 v6, 0xbfb8aa3b, v42
	v_exp_f32_e32 v6, v6
	s_nop 0
	v_add_f32_e32 v6, 1.0, v6
	v_rcp_f32_e32 v6, v6
	s_nop 0
	v_cndmask_b32_e64 v6, v8, v6, s[42:43]
	v_mul_f32_e32 v8, v7, v18
	v_mul_f32_e32 v7, 0xbfb8aa3b, v43
	v_exp_f32_e32 v7, v7
	s_nop 0
	v_add_f32_e32 v7, 1.0, v7
	v_rcp_f32_e32 v7, v7
	s_nop 0
	v_cndmask_b32_e64 v7, v8, v7, s[42:43]
	v_mul_f32_e32 v8, v0, v18
	v_mul_f32_e32 v0, 0xbfb8aa3b, v32
	v_exp_f32_e32 v0, v0
	s_nop 0
	v_add_f32_e32 v0, 1.0, v0
	v_rcp_f32_e32 v0, v0
	s_nop 0
	v_cndmask_b32_e64 v8, v8, v0, s[42:43]
	v_mul_f32_e32 v0, v1, v18
	v_mul_f32_e32 v1, 0xbfb8aa3b, v33
	v_exp_f32_e32 v1, v1
	s_nop 0
	v_add_f32_e32 v1, 1.0, v1
	v_rcp_f32_e32 v1, v1
	s_nop 0
	v_cndmask_b32_e64 v9, v0, v1, s[42:43]
	v_mul_f32_e32 v1, 0xbfb8aa3b, v34
	v_exp_f32_e32 v1, v1
	v_mul_f32_e32 v0, v2, v18
	v_add_f32_e32 v1, 1.0, v1
	v_rcp_f32_e32 v1, v1
	s_nop 0
	v_cndmask_b32_e64 v10, v0, v1, s[42:43]
	v_mul_f32_e32 v1, 0xbfb8aa3b, v35
	v_exp_f32_e32 v1, v1
	v_mul_f32_e32 v0, v3, v18
	v_add_f32_e32 v1, 1.0, v1
	v_rcp_f32_e32 v1, v1
	s_nop 0
	v_cndmask_b32_e64 v3, v0, v1, s[42:43]
	v_cvt_pk_bf16_f32 v0, v4, v5
	v_cvt_pk_bf16_f32 v1, v6, v7
	v_cvt_pk_bf16_f32 v2, v8, v9
	v_cvt_pk_bf16_f32 v3, v10, v3
	global_store_dwordx4 v[16:17], v[0:3], off offset:256 nt
	s_branch .Lmy_p1_join
